# same 8-load de-serialisation applied to the scan-phase loop LBB0_293 (loads into dead VGPRs v70-v97/v168-v175)
# baseline (speedup 1.0000x reference)
.LBB0_293:
	v_lshl_add_u64 v[22:23], v[20:21], 0, s[2:3]
	v_add_co_u32_e32 v176, vcc, s22, v22
	s_nop 1
	v_addc_co_u32_e32 v177, vcc, 0, v23, vcc
	global_load_dwordx4 v[70:73], v[176:177], off
	v_add_co_u32_e32 v176, vcc, 0x2409000, v22
	s_nop 1
	v_addc_co_u32_e32 v177, vcc, 0, v23, vcc
	global_load_dwordx4 v[76:79], v[176:177], off
	v_add_co_u32_e32 v176, vcc, 0x2412000, v22
	s_nop 1
	v_addc_co_u32_e32 v177, vcc, 0, v23, vcc
	global_load_dwordx4 v[80:83], v[176:177], off
	v_add_co_u32_e32 v176, vcc, 0x241b000, v22
	s_nop 1
	v_addc_co_u32_e32 v177, vcc, 0, v23, vcc
	global_load_dwordx4 v[86:89], v[176:177], off
	v_add_co_u32_e32 v176, vcc, 0x2424000, v22
	s_nop 1
	v_addc_co_u32_e32 v177, vcc, 0, v23, vcc
	global_load_dwordx4 v[90:93], v[176:177], off
	v_add_co_u32_e32 v176, vcc, 0x242d000, v22
	s_nop 1
	v_addc_co_u32_e32 v177, vcc, 0, v23, vcc
	global_load_dwordx4 v[94:97], v[176:177], off
	v_add_co_u32_e32 v176, vcc, 0x2436000, v22
	s_nop 1
	v_addc_co_u32_e32 v177, vcc, 0, v23, vcc
	global_load_dwordx4 v[168:171], v[176:177], off
	v_add_co_u32_e32 v176, vcc, 0x243f000, v22
	s_nop 1
	v_addc_co_u32_e32 v177, vcc, 0, v23, vcc
	global_load_dwordx4 v[172:175], v[176:177], off
	v_add_co_u32_e32 v30, vcc, s22, v22
	ds_read_b128 v[26:29], v24
	ds_read_b128 v[2:5], v24 offset:16
	v_addc_co_u32_e32 v31, vcc, 0, v23, vcc
	s_mov_b32 s20, 0x2409000
	s_add_u32 s2, s2, 0x48000
	s_addc_u32 s3, s3, 0
	s_cmp_eq_u32 s2, 0x240000
	s_waitcnt vmcnt(7) lgkmcnt(1)
	v_mov_b64_e32 v[30:31], v[70:71]
	v_mov_b64_e32 v[32:33], v[72:73]
	v_pk_fma_f32 v[34:35], v[30:31], v[26:27], v[6:7] op_sel_hi:[1,0,1]
	v_pk_fma_f32 v[36:37], v[32:33], v[26:27], v[8:9] op_sel_hi:[1,0,1]
	ds_read_b128 v[6:9], v24 offset:4096
	s_waitcnt lgkmcnt(0)
	v_pk_fma_f32 v[38:39], v[30:31], v[6:7], v[14:15] op_sel_hi:[1,0,1]
	v_pk_fma_f32 v[40:41], v[32:33], v[6:7], v[16:17] op_sel_hi:[1,0,1]
	ds_read_b128 v[14:17], v24 offset:8192
	s_waitcnt lgkmcnt(0)
	v_pk_fma_f32 v[30:31], v[30:31], v[14:15], v[10:11] op_sel_hi:[1,0,1]
	v_add_co_u32_e32 v10, vcc, s20, v22
	v_pk_fma_f32 v[32:33], v[32:33], v[14:15], v[12:13] op_sel_hi:[1,0,1]
	s_nop 0
	v_addc_co_u32_e32 v11, vcc, 0, v23, vcc
	s_mov_b32 s20, 0x2412000
	s_waitcnt vmcnt(6)
	v_mov_b64_e32 v[10:11], v[76:77]
	v_mov_b64_e32 v[12:13], v[78:79]
	v_pk_fma_f32 v[34:35], v[10:11], v[26:27], v[34:35] op_sel:[0,1,0]
	v_pk_fma_f32 v[26:27], v[12:13], v[26:27], v[36:37] op_sel:[0,1,0]
	v_pk_fma_f32 v[36:37], v[10:11], v[6:7], v[38:39] op_sel:[0,1,0]
	v_pk_fma_f32 v[30:31], v[10:11], v[14:15], v[30:31] op_sel:[0,1,0]
	v_add_co_u32_e32 v10, vcc, s20, v22
	v_pk_fma_f32 v[6:7], v[12:13], v[6:7], v[40:41] op_sel:[0,1,0]
	s_nop 0
	v_addc_co_u32_e32 v11, vcc, 0, v23, vcc
	v_pk_fma_f32 v[14:15], v[12:13], v[14:15], v[32:33] op_sel:[0,1,0]
	s_mov_b32 s20, 0x241b000
	s_waitcnt vmcnt(5)
	v_mov_b64_e32 v[10:11], v[80:81]
	v_mov_b64_e32 v[12:13], v[82:83]
	v_pk_fma_f32 v[32:33], v[10:11], v[28:29], v[34:35] op_sel_hi:[1,0,1]
	v_pk_fma_f32 v[34:35], v[10:11], v[8:9], v[36:37] op_sel_hi:[1,0,1]
	v_pk_fma_f32 v[30:31], v[10:11], v[16:17], v[30:31] op_sel_hi:[1,0,1]
	v_add_co_u32_e32 v10, vcc, s20, v22
	v_pk_fma_f32 v[26:27], v[12:13], v[28:29], v[26:27] op_sel_hi:[1,0,1]
	s_nop 0
	v_addc_co_u32_e32 v11, vcc, 0, v23, vcc
	v_pk_fma_f32 v[6:7], v[12:13], v[8:9], v[6:7] op_sel_hi:[1,0,1]
	v_pk_fma_f32 v[14:15], v[12:13], v[16:17], v[14:15] op_sel_hi:[1,0,1]
	v_mov_b32_e32 v8, v29
	s_mov_b32 s20, 0x2424000
	s_waitcnt vmcnt(4)
	v_mov_b64_e32 v[10:11], v[86:87]
	v_mov_b64_e32 v[12:13], v[88:89]
	v_pk_fma_f32 v[28:29], v[10:11], v[8:9], v[32:33] op_sel_hi:[1,0,1]
	v_pk_fma_f32 v[26:27], v[12:13], v[8:9], v[26:27] op_sel_hi:[1,0,1]
	v_mov_b32_e32 v8, v9
	v_pk_fma_f32 v[32:33], v[10:11], v[8:9], v[34:35] op_sel_hi:[1,0,1]
	v_pk_fma_f32 v[34:35], v[12:13], v[8:9], v[6:7] op_sel_hi:[1,0,1]
	v_mov_b32_e32 v6, v17
	v_pk_fma_f32 v[16:17], v[10:11], v[6:7], v[30:31] op_sel_hi:[1,0,1]
	v_pk_fma_f32 v[14:15], v[12:13], v[6:7], v[14:15] op_sel_hi:[1,0,1]
	v_add_co_u32_e32 v6, vcc, s20, v22
	ds_read_b128 v[10:13], v24 offset:4112
	s_nop 0
	v_addc_co_u32_e32 v7, vcc, 0, v23, vcc
	s_mov_b32 s20, 0x242d000
	s_waitcnt vmcnt(3)
	v_mov_b64_e32 v[6:7], v[90:91]
	v_mov_b64_e32 v[8:9], v[92:93]
	v_pk_fma_f32 v[30:31], v[6:7], v[2:3], v[28:29] op_sel_hi:[1,0,1]
	v_pk_fma_f32 v[36:37], v[8:9], v[2:3], v[26:27] op_sel_hi:[1,0,1]
	ds_read_b128 v[26:29], v24 offset:8208
	s_waitcnt lgkmcnt(1)
	v_pk_fma_f32 v[32:33], v[6:7], v[10:11], v[32:33] op_sel_hi:[1,0,1]
	v_pk_fma_f32 v[34:35], v[8:9], v[10:11], v[34:35] op_sel_hi:[1,0,1]
	v_add_u32_e32 v24, 32, v24
	s_waitcnt lgkmcnt(0)
	v_pk_fma_f32 v[16:17], v[6:7], v[26:27], v[16:17] op_sel_hi:[1,0,1]
	v_add_co_u32_e32 v6, vcc, s20, v22
	v_pk_fma_f32 v[14:15], v[8:9], v[26:27], v[14:15] op_sel_hi:[1,0,1]
	s_nop 0
	v_addc_co_u32_e32 v7, vcc, 0, v23, vcc
	s_mov_b32 s20, 0x2436000
	s_waitcnt vmcnt(2)
	v_mov_b64_e32 v[6:7], v[94:95]
	v_mov_b64_e32 v[8:9], v[96:97]
	v_pk_fma_f32 v[30:31], v[6:7], v[2:3], v[30:31] op_sel:[0,1,0]
	v_pk_fma_f32 v[32:33], v[6:7], v[10:11], v[32:33] op_sel:[0,1,0]
	v_pk_fma_f32 v[16:17], v[6:7], v[26:27], v[16:17] op_sel:[0,1,0]
	v_add_co_u32_e32 v6, vcc, s20, v22
	v_pk_fma_f32 v[2:3], v[8:9], v[2:3], v[36:37] op_sel:[0,1,0]
	s_nop 0
	v_addc_co_u32_e32 v7, vcc, 0, v23, vcc
	v_pk_fma_f32 v[10:11], v[8:9], v[10:11], v[34:35] op_sel:[0,1,0]
	v_pk_fma_f32 v[14:15], v[8:9], v[26:27], v[14:15] op_sel:[0,1,0]
	s_mov_b32 s20, 0x243f000
	s_waitcnt vmcnt(1)
	v_mov_b64_e32 v[6:7], v[168:169]
	v_mov_b64_e32 v[8:9], v[170:171]
	v_pk_fma_f32 v[26:27], v[6:7], v[4:5], v[30:31] op_sel_hi:[1,0,1]
	v_pk_fma_f32 v[34:35], v[6:7], v[12:13], v[32:33] op_sel_hi:[1,0,1]
	v_pk_fma_f32 v[36:37], v[6:7], v[28:29], v[16:17] op_sel_hi:[1,0,1]
	v_add_co_u32_e32 v6, vcc, s20, v22
	v_pk_fma_f32 v[2:3], v[8:9], v[4:5], v[2:3] op_sel_hi:[1,0,1]
	s_nop 0
	v_addc_co_u32_e32 v7, vcc, 0, v23, vcc
	v_mov_b32_e32 v4, v5
	v_pk_fma_f32 v[10:11], v[8:9], v[12:13], v[10:11] op_sel_hi:[1,0,1]
	v_pk_fma_f32 v[38:39], v[8:9], v[28:29], v[14:15] op_sel_hi:[1,0,1]
	s_waitcnt vmcnt(0)
	v_mov_b64_e32 v[30:31], v[172:173]
	v_mov_b64_e32 v[32:33], v[174:175]
	v_pk_fma_f32 v[8:9], v[32:33], v[4:5], v[2:3] op_sel_hi:[1,0,1]
	v_mov_b32_e32 v2, v13
	v_pk_fma_f32 v[14:15], v[30:31], v[2:3], v[34:35] op_sel_hi:[1,0,1]
	v_pk_fma_f32 v[16:17], v[32:33], v[2:3], v[10:11] op_sel_hi:[1,0,1]
	v_mov_b32_e32 v2, v29
	v_pk_fma_f32 v[6:7], v[30:31], v[4:5], v[26:27] op_sel_hi:[1,0,1]
	v_pk_fma_f32 v[10:11], v[30:31], v[2:3], v[36:37] op_sel_hi:[1,0,1]
	v_pk_fma_f32 v[12:13], v[32:33], v[2:3], v[38:39] op_sel_hi:[1,0,1]
	s_cbranch_scc0 .LBB0_293
	v_readlane_b32 s4, v255, 6
	v_readlane_b32 s5, v255, 7
	ds_write_b128 v235, v[6:9] offset:12288
	ds_write_b128 v235, v[14:17] offset:12544
	ds_write_b128 v235, v[10:13] offset:12800
	s_waitcnt lgkmcnt(0)
	s_barrier
	s_and_saveexec_b64 s[2:3], s[4:5]
	s_cbranch_execz .LBB0_118
	v_add_u32_e32 v6, 1, v0
	s_movk_i32 s20, 0x2400
	v_mad_u64_u32 v[2:3], s[20:21], v6, s20, v[18:19]
	v_or_b32_e32 v2, v2, v106
	v_readlane_b32 s4, v254, 25
	v_ashrrev_i32_e32 v3, 31, v2
	v_readlane_b32 s6, v254, 27
	v_readlane_b32 s7, v254, 28
	ds_read2st64_b32 v[4:5], v236 offset0:51 offset1:54
	v_readlane_b32 s5, v254, 26
	v_lshl_add_u64 v[2:3], v[2:3], 2, s[6:7]
	global_load_dword v0, v[2:3], off
	ds_read2st64_b32 v[2:3], v234 offset0:48 offset1:60
	v_readlane_b32 s8, v254, 29
	v_readlane_b32 s9, v254, 30
	v_readlane_b32 s10, v254, 31
	v_readlane_b32 s11, v254, 32
	v_readlane_b32 s12, v254, 33
	v_readlane_b32 s13, v254, 34
	v_readlane_b32 s14, v254, 35
	v_readlane_b32 s15, v254, 36
	v_readlane_b32 s16, v254, 37
	v_readlane_b32 s17, v254, 38
	v_readlane_b32 s18, v254, 39
	v_readlane_b32 s19, v254, 40
	v_readlane_b32 s4, v253, 33
	v_readlane_b32 s10, v253, 39
	v_readlane_b32 s11, v253, 40
	v_readlane_b32 s5, v253, 34
	v_readlane_b32 s6, v253, 35
	v_readlane_b32 s7, v253, 36
	v_readlane_b32 s8, v253, 37
	v_readlane_b32 s9, v253, 38
	v_readlane_b32 s12, v253, 41
	v_readlane_b32 s13, v253, 42
	v_readlane_b32 s14, v253, 43
	v_readlane_b32 s15, v253, 44
	v_readlane_b32 s16, v253, 45
	v_readlane_b32 s17, v253, 46
	v_readlane_b32 s18, v253, 47
	v_readlane_b32 s19, v253, 48
	s_waitcnt vmcnt(0) lgkmcnt(0)
	v_add_f32_e32 v0, v0, v2
	v_add_f32_e32 v0, v0, v4
	v_add_f32_e32 v0, v0, v5
	ds_read2st64_b32 v[4:5], v236 offset0:57 offset1:63
	s_waitcnt lgkmcnt(0)
	v_add_f32_e32 v0, v0, v4
	v_add_f32_e32 v0, v0, v3
	ds_read2st64_b32 v[2:3], v236 offset0:66 offset1:69
	v_add_f32_e32 v0, v0, v5
	ds_read2st64_b32 v[4:5], v236 offset0:75 offset1:78
	s_waitcnt lgkmcnt(1)
	v_add_f32_e32 v0, v0, v2
	v_add_f32_e32 v0, v0, v3
	ds_read2st64_b32 v[2:3], v234 offset0:72 offset1:84
	s_waitcnt lgkmcnt(0)
	v_add_f32_e32 v0, v0, v2
	v_add_f32_e32 v0, v0, v4
	v_add_f32_e32 v0, v0, v5
	ds_read2st64_b32 v[4:5], v236 offset0:81 offset1:87
	s_waitcnt lgkmcnt(0)
	v_add_f32_e32 v0, v0, v4
	v_add_f32_e32 v0, v0, v3
	ds_read2st64_b32 v[2:3], v236 offset0:90 offset1:93
	v_add_f32_e32 v0, v0, v5
	v_lshlrev_b32_e32 v4, 2, v106
	v_mov_b32_e32 v5, v1
	s_waitcnt lgkmcnt(0)
	v_add_f32_e32 v0, v0, v2
	v_add_f32_e32 v7, v0, v3
	v_and_b32_e32 v0, 12, v185
	v_add_u32_e32 v0, v6, v0
	v_mov_b64_e32 v[2:3], s[10:11]
	v_mad_i64_i32 v[2:3], s[20:21], v0, s30, v[2:3]
	v_lshl_add_u64 v[2:3], v[18:19], 2, v[2:3]
	v_lshl_add_u64 v[2:3], v[2:3], 0, v[4:5]
	global_store_dword v[2:3], v7, off
	s_branch .LBB0_118
